# FFN1 epilogue: packed f32 center-tap FMA and SiLU multiplies, exp2 scale folded into conv weights (fewer VALU instrs)
# speedup vs baseline: 1.0118x; 1.0118x over previous
.LBB0_73:
	s_mov_b32 s30, s75
	v_mov_b32_e32 v133, v181
	s_mov_b32 s1, s85
	v_mov_b32_e32 v132, v185
	s_lshl_b32 s0, s30, 8
	s_lshl_b32 s23, s1, 6
	v_lshlrev_b32_e32 v122, 4, v133
	s_add_i32 s0, s0, s23
	v_add3_u32 v134, s0, v132, v122
	v_bfe_i32 v122, v134, 7, 1
	v_and_b32_e32 v122, 0xb00, v122
	s_lshl_b32 s0, s22, 7
	v_add_u32_e32 v122, s0, v122
	s_movk_i32 s22, 0x7f
	v_and_or_b32 v122, v134, s22, v122
	v_ashrrev_i32_e32 v123, 31, v122
	v_lshlrev_b64 v[124:125], 2, v[122:123]
	v_lshl_add_u64 v[122:123], s[12:13], 0, v[124:125]
	v_ashrrev_i32_e32 v135, 8, v134
	v_lshl_add_u64 v[124:125], s[10:11], 0, v[124:125]
	v_cmp_gt_i32_e32 vcc, 3, v135
	v_mov_b64_e32 v[130:131], v[122:123]
	s_and_saveexec_b64 s[22:23], vcc
	v_mul_hi_i32_i24_e32 v131, 0x5800, v135
	v_mul_i32_i24_e32 v130, 0x5800, v135
	v_lshl_add_u64 v[130:131], v[124:125], 0, v[130:131]
	s_or_b64 exec, exec, s[22:23]
	v_add_u32_e32 v131, 0x200, v134
	v_lshl_add_u32 v130, v134, 2, 0
	v_ashrrev_i32_e32 v131, 8, v131
	v_add_u32_e32 v130, 0x22400, v130
	v_cmp_gt_i32_e32 vcc, 3, v131
	s_and_saveexec_b64 s[22:23], vcc
	v_mul_hi_i32_i24_e32 v123, 0x5800, v131
	v_mul_i32_i24_e32 v122, 0x5800, v131
	v_lshl_add_u64 v[122:123], v[124:125], 0, v[122:123]
	s_or_b64 exec, exec, s[22:23]
	v_cmp_lt_i32_e32 vcc, 14, v132
	v_and_b32_e32 v238, 0x80, v134
	v_mov_b32_e32 v239, 0xbfb8aa3b
	v_cmp_eq_u32_e64 s[100:101], 0, v238
	v_mov_b32_e32 v238, 0xbf317218
	s_nop 1
	v_cndmask_b32_e64 v238, v238, v239, s[100:101]
	v_mul_f32_e32 v248, v248, v238
	v_mul_f32_e32 v249, v249, v238
	ds_write_b32 v130, v248
	ds_write_b32 v130, v249 offset:2048
	v_lshlrev_b32_e32 v122, 3, v133
	v_lshl_add_u32 v172, s1, 5, v122
	s_and_saveexec_b64 s[22:23], vcc
	s_xor_b64 s[22:23], exec, s[22:23]
	s_cbranch_execz .LBB0_81
	v_cmp_eq_u32_e32 vcc, 15, v132
	s_and_saveexec_b64 s[26:27], vcc
	s_cbranch_execz .LBB0_80
	s_lshl_b32 s1, s30, 11
	s_add_i32 s1, s1, 0
	s_add_i32 s1, s1, 0x20000
	v_lshl_add_u32 v122, v172, 2, s1
	ds_write_b128 v122, v[102:105] offset:1024
	ds_write_b128 v122, v[38:41] offset:1040
	ds_write_b128 v122, v[98:101] offset:1536
	ds_write_b128 v122, v[34:37] offset:1552

.LBB0_97:
	s_or_b64 exec, exec, s[22:23]
	s_cmp_gt_i32 s30, 0
	s_waitcnt lgkmcnt(0)
	s_barrier
	v_cmp_eq_u32_e64 s[42:43], 0, v132
	v_cmp_eq_u32_e64 s[40:41], 15, v132
	v_mov_b32_e32 v236, 1.0
	v_lshlrev_b32_e32 v230, 2, v172
	v_add_u32_e32 v230, 0x22400, v230
	s_lshl_b32 s100, s29, 8
	s_lshl_b32 s101, s30, 6
	s_add_i32 s100, s100, s101
	v_add_u32_e32 v231, s100, v132
	v_mov_b64_e32 v[232:233], s[16:17]
	v_mad_i64_i32 v[232:233], vcc, v231, s15, v[232:233]
	s_lshl_b64 s[100:101], s[0:1], 1
	v_lshl_add_u64 v[232:233], v[232:233], 0, s[100:101]
	v_lshlrev_b64 v[228:229], 1, v[172:173]
	v_lshl_add_u64 v[232:233], v[232:233], 0, v[228:229]
	ds_read_b128 v[190:193], v230 offset:0
	ds_read_b128 v[194:197], v230 offset:512
	ds_read_b128 v[198:201], v230 offset:1024
	ds_read_b128 v[208:211], v230 offset:1536
	ds_read_b128 v[212:215], v230 offset:2048
	ds_read_b128 v[216:219], v230 offset:2560
	ds_read_b128 v[220:223], v230 offset:3072
	ds_read_b128 v[224:227], v230 offset:3584
	s_cmp_eq_u32 s30, 0
	s_cbranch_scc1 .Lffn1c_1
	s_lshl_b32 s100, s30, 11
	s_sub_i32 s100, s100, 0x400
	v_add_u32_e32 v231, s100, v189
	ds_read_b128 v[130:133], v231 offset:0
	ds_read_b128 v[134:137], v231 offset:512
	s_branch .Lffn1c_2

.Lffn1c_2:
	s_lshl_b32 s100, s30, 11
	s_add_i32 s100, s100, 0x800
	v_add_u32_e32 v231, s100, v189
	ds_read_b128 v[138:141], v231 offset:0
	ds_read_b128 v[142:145], v231 offset:512
	s_waitcnt lgkmcnt(0)
	v_cndmask_b32_e64 v150, v126, v130, s[40:41]
	v_cndmask_b32_e64 v151, v127, v131, s[40:41]
	v_cndmask_b32_e64 v152, v128, v132, s[40:41]
	v_cndmask_b32_e64 v153, v129, v133, s[40:41]
	v_cndmask_b32_e64 v154, v126, v118, s[42:43]
	v_cndmask_b32_e64 v155, v127, v119, s[42:43]
	v_cndmask_b32_e64 v156, v128, v120, s[42:43]
	v_cndmask_b32_e64 v157, v129, v121, s[42:43]
	v_pk_fma_f32 v[122:123], v[126:127], v[198:199], v[220:221]
	v_pk_fma_f32 v[124:125], v[128:129], v[200:201], v[222:223]
	v_fmac_f32_dpp v122, v150, v190 row_ror:1 row_mask:0xf bank_mask:0xf
	v_fmac_f32_dpp v123, v151, v191 row_ror:1 row_mask:0xf bank_mask:0xf
	v_fmac_f32_dpp v124, v152, v192 row_ror:1 row_mask:0xf bank_mask:0xf
	v_fmac_f32_dpp v125, v153, v193 row_ror:1 row_mask:0xf bank_mask:0xf
	v_fmac_f32_dpp v122, v154, v212 row_ror:15 row_mask:0xf bank_mask:0xf
	v_fmac_f32_dpp v123, v155, v213 row_ror:15 row_mask:0xf bank_mask:0xf
	v_fmac_f32_dpp v124, v156, v214 row_ror:15 row_mask:0xf bank_mask:0xf
	v_fmac_f32_dpp v125, v157, v215 row_ror:15 row_mask:0xf bank_mask:0xf
	v_cndmask_b32_e64 v150, v146, v134, s[40:41]
	v_cndmask_b32_e64 v151, v147, v135, s[40:41]
	v_cndmask_b32_e64 v152, v148, v136, s[40:41]
	v_cndmask_b32_e64 v153, v149, v137, s[40:41]
	v_cndmask_b32_e64 v154, v146, v114, s[42:43]
	v_cndmask_b32_e64 v155, v147, v115, s[42:43]
	v_cndmask_b32_e64 v156, v148, v116, s[42:43]
	v_cndmask_b32_e64 v157, v149, v117, s[42:43]
	v_pk_fma_f32 v[158:159], v[146:147], v[208:209], v[224:225]
	v_pk_fma_f32 v[160:161], v[148:149], v[210:211], v[226:227]
	v_fmac_f32_dpp v158, v150, v194 row_ror:1 row_mask:0xf bank_mask:0xf
	v_fmac_f32_dpp v159, v151, v195 row_ror:1 row_mask:0xf bank_mask:0xf
	v_fmac_f32_dpp v160, v152, v196 row_ror:1 row_mask:0xf bank_mask:0xf
	v_fmac_f32_dpp v161, v153, v197 row_ror:1 row_mask:0xf bank_mask:0xf
	v_fmac_f32_dpp v158, v154, v216 row_ror:15 row_mask:0xf bank_mask:0xf
	v_fmac_f32_dpp v159, v155, v217 row_ror:15 row_mask:0xf bank_mask:0xf
	v_fmac_f32_dpp v160, v156, v218 row_ror:15 row_mask:0xf bank_mask:0xf
	v_fmac_f32_dpp v161, v157, v219 row_ror:15 row_mask:0xf bank_mask:0xf
	s_lshl_b32 s100, s30, 11
	s_add_i32 s100, s100, 0xc00
	v_add_u32_e32 v231, s100, v189
	ds_read_b128 v[130:133], v231 offset:0
	ds_read_b128 v[134:137], v231 offset:512
	v_exp_f32_e32 v172, v122
	v_exp_f32_e32 v173, v123
	v_exp_f32_e32 v174, v124
	v_exp_f32_e32 v175, v125
	v_pk_add_f32 v[172:173], v[172:173], v[236:237] op_sel_hi:[1,0]
	v_pk_add_f32 v[174:175], v[174:175], v[236:237] op_sel_hi:[1,0]
	v_rcp_f32_e32 v172, v172
	v_rcp_f32_e32 v173, v173
	v_rcp_f32_e32 v174, v174
	v_rcp_f32_e32 v175, v175
	v_mov_b64_e32 v[234:235], v[232:233]
	v_pk_mul_f32 v[122:123], v[122:123], v[158:159]
	v_pk_mul_f32 v[124:125], v[124:125], v[160:161]
	v_pk_mul_f32 v[172:173], v[172:173], v[122:123]
	v_pk_mul_f32 v[174:175], v[174:175], v[124:125]
	v_cvt_pk_bf16_f32 v228, v172, v173
	v_cvt_pk_bf16_f32 v229, v174, v175
	global_store_dwordx2 v[234:235], v[228:229], off
	v_cndmask_b32_e64 v150, v118, v126, s[40:41]
	v_cndmask_b32_e64 v151, v119, v127, s[40:41]
	v_cndmask_b32_e64 v152, v120, v128, s[40:41]
	v_cndmask_b32_e64 v153, v121, v129, s[40:41]
	v_cndmask_b32_e64 v154, v118, v110, s[42:43]
	v_cndmask_b32_e64 v155, v119, v111, s[42:43]
	v_cndmask_b32_e64 v156, v120, v112, s[42:43]
	v_cndmask_b32_e64 v157, v121, v113, s[42:43]
	v_pk_fma_f32 v[122:123], v[118:119], v[198:199], v[220:221]
	v_pk_fma_f32 v[124:125], v[120:121], v[200:201], v[222:223]
	v_fmac_f32_dpp v122, v150, v190 row_ror:1 row_mask:0xf bank_mask:0xf
	v_fmac_f32_dpp v123, v151, v191 row_ror:1 row_mask:0xf bank_mask:0xf
	v_fmac_f32_dpp v124, v152, v192 row_ror:1 row_mask:0xf bank_mask:0xf
	v_fmac_f32_dpp v125, v153, v193 row_ror:1 row_mask:0xf bank_mask:0xf
	v_fmac_f32_dpp v122, v154, v212 row_ror:15 row_mask:0xf bank_mask:0xf
	v_fmac_f32_dpp v123, v155, v213 row_ror:15 row_mask:0xf bank_mask:0xf
	v_fmac_f32_dpp v124, v156, v214 row_ror:15 row_mask:0xf bank_mask:0xf
	v_fmac_f32_dpp v125, v157, v215 row_ror:15 row_mask:0xf bank_mask:0xf
	v_cndmask_b32_e64 v150, v114, v146, s[40:41]
	v_cndmask_b32_e64 v151, v115, v147, s[40:41]
	v_cndmask_b32_e64 v152, v116, v148, s[40:41]
	v_cndmask_b32_e64 v153, v117, v149, s[40:41]
	v_cndmask_b32_e64 v154, v114, v106, s[42:43]
	v_cndmask_b32_e64 v155, v115, v107, s[42:43]
	v_cndmask_b32_e64 v156, v116, v108, s[42:43]
	v_cndmask_b32_e64 v157, v117, v109, s[42:43]
	v_pk_fma_f32 v[158:159], v[114:115], v[208:209], v[224:225]
	v_pk_fma_f32 v[160:161], v[116:117], v[210:211], v[226:227]
	v_fmac_f32_dpp v158, v150, v194 row_ror:1 row_mask:0xf bank_mask:0xf
	v_fmac_f32_dpp v159, v151, v195 row_ror:1 row_mask:0xf bank_mask:0xf
	v_fmac_f32_dpp v160, v152, v196 row_ror:1 row_mask:0xf bank_mask:0xf
	v_fmac_f32_dpp v161, v153, v197 row_ror:1 row_mask:0xf bank_mask:0xf
	v_fmac_f32_dpp v158, v154, v216 row_ror:15 row_mask:0xf bank_mask:0xf
	v_fmac_f32_dpp v159, v155, v217 row_ror:15 row_mask:0xf bank_mask:0xf
	v_fmac_f32_dpp v160, v156, v218 row_ror:15 row_mask:0xf bank_mask:0xf
	v_fmac_f32_dpp v161, v157, v219 row_ror:15 row_mask:0xf bank_mask:0xf
	v_exp_f32_e32 v172, v122
	v_exp_f32_e32 v173, v123
	v_exp_f32_e32 v174, v124
	v_exp_f32_e32 v175, v125
	v_pk_add_f32 v[172:173], v[172:173], v[236:237] op_sel_hi:[1,0]
	v_pk_add_f32 v[174:175], v[174:175], v[236:237] op_sel_hi:[1,0]
	v_rcp_f32_e32 v172, v172
	v_rcp_f32_e32 v173, v173
	v_rcp_f32_e32 v174, v174
	v_rcp_f32_e32 v175, v175
	s_mov_b64 s[100:101], 0x16000
	v_lshl_add_u64 v[234:235], v[232:233], 0, s[100:101]
	v_pk_mul_f32 v[122:123], v[122:123], v[158:159]
	v_pk_mul_f32 v[124:125], v[124:125], v[160:161]
	v_pk_mul_f32 v[172:173], v[172:173], v[122:123]
	v_pk_mul_f32 v[174:175], v[174:175], v[124:125]
	v_cvt_pk_bf16_f32 v228, v172, v173
	v_cvt_pk_bf16_f32 v229, v174, v175
	global_store_dwordx2 v[234:235], v[228:229], off
	v_cndmask_b32_e64 v150, v110, v118, s[40:41]
	v_cndmask_b32_e64 v151, v111, v119, s[40:41]
	v_cndmask_b32_e64 v152, v112, v120, s[40:41]
	v_cndmask_b32_e64 v153, v113, v121, s[40:41]
	v_cndmask_b32_e64 v154, v110, v102, s[42:43]
	v_cndmask_b32_e64 v155, v111, v103, s[42:43]
	v_cndmask_b32_e64 v156, v112, v104, s[42:43]
	v_cndmask_b32_e64 v157, v113, v105, s[42:43]
	v_pk_fma_f32 v[122:123], v[110:111], v[198:199], v[220:221]
	v_pk_fma_f32 v[124:125], v[112:113], v[200:201], v[222:223]
	v_fmac_f32_dpp v122, v150, v190 row_ror:1 row_mask:0xf bank_mask:0xf
	v_fmac_f32_dpp v123, v151, v191 row_ror:1 row_mask:0xf bank_mask:0xf
	v_fmac_f32_dpp v124, v152, v192 row_ror:1 row_mask:0xf bank_mask:0xf
	v_fmac_f32_dpp v125, v153, v193 row_ror:1 row_mask:0xf bank_mask:0xf
	v_fmac_f32_dpp v122, v154, v212 row_ror:15 row_mask:0xf bank_mask:0xf
	v_fmac_f32_dpp v123, v155, v213 row_ror:15 row_mask:0xf bank_mask:0xf
	v_fmac_f32_dpp v124, v156, v214 row_ror:15 row_mask:0xf bank_mask:0xf
	v_fmac_f32_dpp v125, v157, v215 row_ror:15 row_mask:0xf bank_mask:0xf
	v_cndmask_b32_e64 v150, v106, v114, s[40:41]
	v_cndmask_b32_e64 v151, v107, v115, s[40:41]
	v_cndmask_b32_e64 v152, v108, v116, s[40:41]
	v_cndmask_b32_e64 v153, v109, v117, s[40:41]
	v_cndmask_b32_e64 v154, v106, v98, s[42:43]
	v_cndmask_b32_e64 v155, v107, v99, s[42:43]
	v_cndmask_b32_e64 v156, v108, v100, s[42:43]
	v_cndmask_b32_e64 v157, v109, v101, s[42:43]
	v_pk_fma_f32 v[158:159], v[106:107], v[208:209], v[224:225]
	v_pk_fma_f32 v[160:161], v[108:109], v[210:211], v[226:227]
	v_fmac_f32_dpp v158, v150, v194 row_ror:1 row_mask:0xf bank_mask:0xf
	v_fmac_f32_dpp v159, v151, v195 row_ror:1 row_mask:0xf bank_mask:0xf
	v_fmac_f32_dpp v160, v152, v196 row_ror:1 row_mask:0xf bank_mask:0xf
	v_fmac_f32_dpp v161, v153, v197 row_ror:1 row_mask:0xf bank_mask:0xf
	v_fmac_f32_dpp v158, v154, v216 row_ror:15 row_mask:0xf bank_mask:0xf
	v_fmac_f32_dpp v159, v155, v217 row_ror:15 row_mask:0xf bank_mask:0xf
	v_fmac_f32_dpp v160, v156, v218 row_ror:15 row_mask:0xf bank_mask:0xf
	v_fmac_f32_dpp v161, v157, v219 row_ror:15 row_mask:0xf bank_mask:0xf
	v_exp_f32_e32 v172, v122
	v_exp_f32_e32 v173, v123
	v_exp_f32_e32 v174, v124
	v_exp_f32_e32 v175, v125
	v_pk_add_f32 v[172:173], v[172:173], v[236:237] op_sel_hi:[1,0]
	v_pk_add_f32 v[174:175], v[174:175], v[236:237] op_sel_hi:[1,0]
	v_rcp_f32_e32 v172, v172
	v_rcp_f32_e32 v173, v173
	v_rcp_f32_e32 v174, v174
	v_rcp_f32_e32 v175, v175
	s_mov_b64 s[100:101], 0x2c000
	v_lshl_add_u64 v[234:235], v[232:233], 0, s[100:101]
	v_pk_mul_f32 v[122:123], v[122:123], v[158:159]
	v_pk_mul_f32 v[124:125], v[124:125], v[160:161]
	v_pk_mul_f32 v[172:173], v[172:173], v[122:123]
	v_pk_mul_f32 v[174:175], v[174:175], v[124:125]
	v_cvt_pk_bf16_f32 v228, v172, v173
	v_cvt_pk_bf16_f32 v229, v174, v175
	global_store_dwordx2 v[234:235], v[228:229], off
	s_waitcnt lgkmcnt(0)
	v_cndmask_b32_e64 v150, v102, v110, s[40:41]
	v_cndmask_b32_e64 v151, v103, v111, s[40:41]
	v_cndmask_b32_e64 v152, v104, v112, s[40:41]
	v_cndmask_b32_e64 v153, v105, v113, s[40:41]
	v_cndmask_b32_e64 v154, v102, v138, s[42:43]
	v_cndmask_b32_e64 v155, v103, v139, s[42:43]
	v_cndmask_b32_e64 v156, v104, v140, s[42:43]
	v_cndmask_b32_e64 v157, v105, v141, s[42:43]
	v_pk_fma_f32 v[122:123], v[102:103], v[198:199], v[220:221]
	v_pk_fma_f32 v[124:125], v[104:105], v[200:201], v[222:223]
	v_fmac_f32_dpp v122, v150, v190 row_ror:1 row_mask:0xf bank_mask:0xf
	v_fmac_f32_dpp v123, v151, v191 row_ror:1 row_mask:0xf bank_mask:0xf
	v_fmac_f32_dpp v124, v152, v192 row_ror:1 row_mask:0xf bank_mask:0xf
	v_fmac_f32_dpp v125, v153, v193 row_ror:1 row_mask:0xf bank_mask:0xf
	v_fmac_f32_dpp v122, v154, v212 row_ror:15 row_mask:0xf bank_mask:0xf
	v_fmac_f32_dpp v123, v155, v213 row_ror:15 row_mask:0xf bank_mask:0xf
	v_fmac_f32_dpp v124, v156, v214 row_ror:15 row_mask:0xf bank_mask:0xf
	v_fmac_f32_dpp v125, v157, v215 row_ror:15 row_mask:0xf bank_mask:0xf
	v_cndmask_b32_e64 v150, v98, v106, s[40:41]
	v_cndmask_b32_e64 v151, v99, v107, s[40:41]
	v_cndmask_b32_e64 v152, v100, v108, s[40:41]
	v_cndmask_b32_e64 v153, v101, v109, s[40:41]
	v_cndmask_b32_e64 v154, v98, v142, s[42:43]
	v_cndmask_b32_e64 v155, v99, v143, s[42:43]
	v_cndmask_b32_e64 v156, v100, v144, s[42:43]
	v_cndmask_b32_e64 v157, v101, v145, s[42:43]
	v_pk_fma_f32 v[158:159], v[98:99], v[208:209], v[224:225]
	v_pk_fma_f32 v[160:161], v[100:101], v[210:211], v[226:227]
	v_fmac_f32_dpp v158, v150, v194 row_ror:1 row_mask:0xf bank_mask:0xf
	v_fmac_f32_dpp v159, v151, v195 row_ror:1 row_mask:0xf bank_mask:0xf
	v_fmac_f32_dpp v160, v152, v196 row_ror:1 row_mask:0xf bank_mask:0xf
	v_fmac_f32_dpp v161, v153, v197 row_ror:1 row_mask:0xf bank_mask:0xf
	v_fmac_f32_dpp v158, v154, v216 row_ror:15 row_mask:0xf bank_mask:0xf
	v_fmac_f32_dpp v159, v155, v217 row_ror:15 row_mask:0xf bank_mask:0xf
	v_fmac_f32_dpp v160, v156, v218 row_ror:15 row_mask:0xf bank_mask:0xf
	v_fmac_f32_dpp v161, v157, v219 row_ror:15 row_mask:0xf bank_mask:0xf
	s_cmp_eq_u32 s30, 1
	s_cbranch_scc1 .Lffn1c_3
	s_lshl_b32 s100, s30, 11
	s_add_i32 s100, s100, 0x1800
	v_add_u32_e32 v231, s100, v189
	ds_read_b128 v[138:141], v231 offset:0
	ds_read_b128 v[142:145], v231 offset:512
	s_branch .Lffn1c_4

.Lffn1c_4:
	ds_read_b128 v[126:129], v230 offset:16
	ds_read_b128 v[146:149], v230 offset:528
	ds_read_b128 v[118:121], v230 offset:1040
	ds_read_b128 v[114:117], v230 offset:1552
	ds_read_b128 v[110:113], v230 offset:2064
	ds_read_b128 v[106:109], v230 offset:2576
	ds_read_b128 v[102:105], v230 offset:3088
	ds_read_b128 v[98:101], v230 offset:3600
	v_exp_f32_e32 v172, v122
	v_exp_f32_e32 v173, v123
	v_exp_f32_e32 v174, v124
	v_exp_f32_e32 v175, v125
	v_pk_add_f32 v[172:173], v[172:173], v[236:237] op_sel_hi:[1,0]
	v_pk_add_f32 v[174:175], v[174:175], v[236:237] op_sel_hi:[1,0]
	v_rcp_f32_e32 v172, v172
	v_rcp_f32_e32 v173, v173
	v_rcp_f32_e32 v174, v174
	v_rcp_f32_e32 v175, v175
	s_mov_b64 s[100:101], 0x42000
	v_lshl_add_u64 v[234:235], v[232:233], 0, s[100:101]
	v_pk_mul_f32 v[122:123], v[122:123], v[158:159]
	v_pk_mul_f32 v[124:125], v[124:125], v[160:161]
	v_pk_mul_f32 v[172:173], v[172:173], v[122:123]
	v_pk_mul_f32 v[174:175], v[174:175], v[124:125]
	v_cvt_pk_bf16_f32 v228, v172, v173
	v_cvt_pk_bf16_f32 v229, v174, v175
	global_store_dwordx2 v[234:235], v[228:229], off
	s_waitcnt lgkmcnt(0)
	v_cndmask_b32_e64 v150, v94, v130, s[40:41]
	v_cndmask_b32_e64 v151, v95, v131, s[40:41]
	v_cndmask_b32_e64 v152, v96, v132, s[40:41]
	v_cndmask_b32_e64 v153, v97, v133, s[40:41]
	v_cndmask_b32_e64 v154, v94, v86, s[42:43]
	v_cndmask_b32_e64 v155, v95, v87, s[42:43]
	v_cndmask_b32_e64 v156, v96, v88, s[42:43]
	v_cndmask_b32_e64 v157, v97, v89, s[42:43]
	v_pk_fma_f32 v[122:123], v[94:95], v[198:199], v[220:221]
	v_pk_fma_f32 v[124:125], v[96:97], v[200:201], v[222:223]
	v_fmac_f32_dpp v122, v150, v190 row_ror:1 row_mask:0xf bank_mask:0xf
	v_fmac_f32_dpp v123, v151, v191 row_ror:1 row_mask:0xf bank_mask:0xf
	v_fmac_f32_dpp v124, v152, v192 row_ror:1 row_mask:0xf bank_mask:0xf
	v_fmac_f32_dpp v125, v153, v193 row_ror:1 row_mask:0xf bank_mask:0xf
	v_fmac_f32_dpp v122, v154, v212 row_ror:15 row_mask:0xf bank_mask:0xf
	v_fmac_f32_dpp v123, v155, v213 row_ror:15 row_mask:0xf bank_mask:0xf
	v_fmac_f32_dpp v124, v156, v214 row_ror:15 row_mask:0xf bank_mask:0xf
	v_fmac_f32_dpp v125, v157, v215 row_ror:15 row_mask:0xf bank_mask:0xf
	v_cndmask_b32_e64 v150, v90, v134, s[40:41]
	v_cndmask_b32_e64 v151, v91, v135, s[40:41]
	v_cndmask_b32_e64 v152, v92, v136, s[40:41]
	v_cndmask_b32_e64 v153, v93, v137, s[40:41]
	v_cndmask_b32_e64 v154, v90, v82, s[42:43]
	v_cndmask_b32_e64 v155, v91, v83, s[42:43]
	v_cndmask_b32_e64 v156, v92, v84, s[42:43]
	v_cndmask_b32_e64 v157, v93, v85, s[42:43]
	v_pk_fma_f32 v[158:159], v[90:91], v[208:209], v[224:225]
	v_pk_fma_f32 v[160:161], v[92:93], v[210:211], v[226:227]
	v_fmac_f32_dpp v158, v150, v194 row_ror:1 row_mask:0xf bank_mask:0xf
	v_fmac_f32_dpp v159, v151, v195 row_ror:1 row_mask:0xf bank_mask:0xf
	v_fmac_f32_dpp v160, v152, v196 row_ror:1 row_mask:0xf bank_mask:0xf
	v_fmac_f32_dpp v161, v153, v197 row_ror:1 row_mask:0xf bank_mask:0xf
	v_fmac_f32_dpp v158, v154, v216 row_ror:15 row_mask:0xf bank_mask:0xf
	v_fmac_f32_dpp v159, v155, v217 row_ror:15 row_mask:0xf bank_mask:0xf
	v_fmac_f32_dpp v160, v156, v218 row_ror:15 row_mask:0xf bank_mask:0xf
	v_fmac_f32_dpp v161, v157, v219 row_ror:15 row_mask:0xf bank_mask:0xf
	s_cmp_eq_u32 s30, 0
	s_cbranch_scc1 .Lffn1c_5
	s_lshl_b32 s100, s30, 11
	s_sub_i32 s100, s100, 0x400
	v_add_u32_e32 v231, s100, v189
	ds_read_b128 v[130:133], v231 offset:16
	ds_read_b128 v[134:137], v231 offset:528
	s_branch .Lffn1c_6

.Lffn1c_6:
	v_exp_f32_e32 v172, v122
	v_exp_f32_e32 v173, v123
	v_exp_f32_e32 v174, v124
	v_exp_f32_e32 v175, v125
	v_pk_add_f32 v[172:173], v[172:173], v[236:237] op_sel_hi:[1,0]
	v_pk_add_f32 v[174:175], v[174:175], v[236:237] op_sel_hi:[1,0]
	v_rcp_f32_e32 v172, v172
	v_rcp_f32_e32 v173, v173
	v_rcp_f32_e32 v174, v174
	v_rcp_f32_e32 v175, v175
	s_mov_b64 s[100:101], 0xb0000
	v_lshl_add_u64 v[234:235], v[232:233], 0, s[100:101]
	v_pk_mul_f32 v[122:123], v[122:123], v[158:159]
	v_pk_mul_f32 v[124:125], v[124:125], v[160:161]
	v_pk_mul_f32 v[172:173], v[172:173], v[122:123]
	v_pk_mul_f32 v[174:175], v[174:175], v[124:125]
	v_cvt_pk_bf16_f32 v228, v172, v173
	v_cvt_pk_bf16_f32 v229, v174, v175
	global_store_dwordx2 v[234:235], v[228:229], off
	v_cndmask_b32_e64 v150, v86, v94, s[40:41]
	v_cndmask_b32_e64 v151, v87, v95, s[40:41]
	v_cndmask_b32_e64 v152, v88, v96, s[40:41]
	v_cndmask_b32_e64 v153, v89, v97, s[40:41]
	v_cndmask_b32_e64 v154, v86, v78, s[42:43]
	v_cndmask_b32_e64 v155, v87, v79, s[42:43]
	v_cndmask_b32_e64 v156, v88, v80, s[42:43]
	v_cndmask_b32_e64 v157, v89, v81, s[42:43]
	v_pk_fma_f32 v[122:123], v[86:87], v[198:199], v[220:221]
	v_pk_fma_f32 v[124:125], v[88:89], v[200:201], v[222:223]
	v_fmac_f32_dpp v122, v150, v190 row_ror:1 row_mask:0xf bank_mask:0xf
	v_fmac_f32_dpp v123, v151, v191 row_ror:1 row_mask:0xf bank_mask:0xf
	v_fmac_f32_dpp v124, v152, v192 row_ror:1 row_mask:0xf bank_mask:0xf
	v_fmac_f32_dpp v125, v153, v193 row_ror:1 row_mask:0xf bank_mask:0xf
	v_fmac_f32_dpp v122, v154, v212 row_ror:15 row_mask:0xf bank_mask:0xf
	v_fmac_f32_dpp v123, v155, v213 row_ror:15 row_mask:0xf bank_mask:0xf
	v_fmac_f32_dpp v124, v156, v214 row_ror:15 row_mask:0xf bank_mask:0xf
	v_fmac_f32_dpp v125, v157, v215 row_ror:15 row_mask:0xf bank_mask:0xf
	v_cndmask_b32_e64 v150, v82, v90, s[40:41]
	v_cndmask_b32_e64 v151, v83, v91, s[40:41]
	v_cndmask_b32_e64 v152, v84, v92, s[40:41]
	v_cndmask_b32_e64 v153, v85, v93, s[40:41]
	v_cndmask_b32_e64 v154, v82, v74, s[42:43]
	v_cndmask_b32_e64 v155, v83, v75, s[42:43]
	v_cndmask_b32_e64 v156, v84, v76, s[42:43]
	v_cndmask_b32_e64 v157, v85, v77, s[42:43]
	v_pk_fma_f32 v[158:159], v[82:83], v[208:209], v[224:225]
	v_pk_fma_f32 v[160:161], v[84:85], v[210:211], v[226:227]
	v_fmac_f32_dpp v158, v150, v194 row_ror:1 row_mask:0xf bank_mask:0xf
	v_fmac_f32_dpp v159, v151, v195 row_ror:1 row_mask:0xf bank_mask:0xf
	v_fmac_f32_dpp v160, v152, v196 row_ror:1 row_mask:0xf bank_mask:0xf
	v_fmac_f32_dpp v161, v153, v197 row_ror:1 row_mask:0xf bank_mask:0xf
	v_fmac_f32_dpp v158, v154, v216 row_ror:15 row_mask:0xf bank_mask:0xf
	v_fmac_f32_dpp v159, v155, v217 row_ror:15 row_mask:0xf bank_mask:0xf
	v_fmac_f32_dpp v160, v156, v218 row_ror:15 row_mask:0xf bank_mask:0xf
	v_fmac_f32_dpp v161, v157, v219 row_ror:15 row_mask:0xf bank_mask:0xf
	v_exp_f32_e32 v172, v122
	v_exp_f32_e32 v173, v123
	v_exp_f32_e32 v174, v124
	v_exp_f32_e32 v175, v125
	v_pk_add_f32 v[172:173], v[172:173], v[236:237] op_sel_hi:[1,0]
	v_pk_add_f32 v[174:175], v[174:175], v[236:237] op_sel_hi:[1,0]
	v_rcp_f32_e32 v172, v172
	v_rcp_f32_e32 v173, v173
	v_rcp_f32_e32 v174, v174
	v_rcp_f32_e32 v175, v175
	s_mov_b64 s[100:101], 0xc6000
	v_lshl_add_u64 v[234:235], v[232:233], 0, s[100:101]
	v_pk_mul_f32 v[122:123], v[122:123], v[158:159]
	v_pk_mul_f32 v[124:125], v[124:125], v[160:161]
	v_pk_mul_f32 v[172:173], v[172:173], v[122:123]
	v_pk_mul_f32 v[174:175], v[174:175], v[124:125]
	v_cvt_pk_bf16_f32 v228, v172, v173
	v_cvt_pk_bf16_f32 v229, v174, v175
	global_store_dwordx2 v[234:235], v[228:229], off
	v_cndmask_b32_e64 v150, v78, v86, s[40:41]
	v_cndmask_b32_e64 v151, v79, v87, s[40:41]
	v_cndmask_b32_e64 v152, v80, v88, s[40:41]
	v_cndmask_b32_e64 v153, v81, v89, s[40:41]
	v_cndmask_b32_e64 v154, v78, v70, s[42:43]
	v_cndmask_b32_e64 v155, v79, v71, s[42:43]
	v_cndmask_b32_e64 v156, v80, v72, s[42:43]
	v_cndmask_b32_e64 v157, v81, v73, s[42:43]
	v_pk_fma_f32 v[122:123], v[78:79], v[198:199], v[220:221]
	v_pk_fma_f32 v[124:125], v[80:81], v[200:201], v[222:223]
	v_fmac_f32_dpp v122, v150, v190 row_ror:1 row_mask:0xf bank_mask:0xf
	v_fmac_f32_dpp v123, v151, v191 row_ror:1 row_mask:0xf bank_mask:0xf
	v_fmac_f32_dpp v124, v152, v192 row_ror:1 row_mask:0xf bank_mask:0xf
	v_fmac_f32_dpp v125, v153, v193 row_ror:1 row_mask:0xf bank_mask:0xf
	v_fmac_f32_dpp v122, v154, v212 row_ror:15 row_mask:0xf bank_mask:0xf
	v_fmac_f32_dpp v123, v155, v213 row_ror:15 row_mask:0xf bank_mask:0xf
	v_fmac_f32_dpp v124, v156, v214 row_ror:15 row_mask:0xf bank_mask:0xf
	v_fmac_f32_dpp v125, v157, v215 row_ror:15 row_mask:0xf bank_mask:0xf
	v_cndmask_b32_e64 v150, v74, v82, s[40:41]
	v_cndmask_b32_e64 v151, v75, v83, s[40:41]
	v_cndmask_b32_e64 v152, v76, v84, s[40:41]
	v_cndmask_b32_e64 v153, v77, v85, s[40:41]
	v_cndmask_b32_e64 v154, v74, v66, s[42:43]
	v_cndmask_b32_e64 v155, v75, v67, s[42:43]
	v_cndmask_b32_e64 v156, v76, v68, s[42:43]
	v_cndmask_b32_e64 v157, v77, v69, s[42:43]
	v_pk_fma_f32 v[158:159], v[74:75], v[208:209], v[224:225]
	v_pk_fma_f32 v[160:161], v[76:77], v[210:211], v[226:227]
	v_fmac_f32_dpp v158, v150, v194 row_ror:1 row_mask:0xf bank_mask:0xf
	v_fmac_f32_dpp v159, v151, v195 row_ror:1 row_mask:0xf bank_mask:0xf
	v_fmac_f32_dpp v160, v152, v196 row_ror:1 row_mask:0xf bank_mask:0xf
	v_fmac_f32_dpp v161, v153, v197 row_ror:1 row_mask:0xf bank_mask:0xf
	v_fmac_f32_dpp v158, v154, v216 row_ror:15 row_mask:0xf bank_mask:0xf
	v_fmac_f32_dpp v159, v155, v217 row_ror:15 row_mask:0xf bank_mask:0xf
	v_fmac_f32_dpp v160, v156, v218 row_ror:15 row_mask:0xf bank_mask:0xf
	v_fmac_f32_dpp v161, v157, v219 row_ror:15 row_mask:0xf bank_mask:0xf
	v_exp_f32_e32 v172, v122
	v_exp_f32_e32 v173, v123
	v_exp_f32_e32 v174, v124
	v_exp_f32_e32 v175, v125
	v_pk_add_f32 v[172:173], v[172:173], v[236:237] op_sel_hi:[1,0]
	v_pk_add_f32 v[174:175], v[174:175], v[236:237] op_sel_hi:[1,0]
	v_rcp_f32_e32 v172, v172
	v_rcp_f32_e32 v173, v173
	v_rcp_f32_e32 v174, v174
	v_rcp_f32_e32 v175, v175
	s_mov_b64 s[100:101], 0xdc000
	v_lshl_add_u64 v[234:235], v[232:233], 0, s[100:101]
	v_pk_mul_f32 v[122:123], v[122:123], v[158:159]
	v_pk_mul_f32 v[124:125], v[124:125], v[160:161]
	v_pk_mul_f32 v[172:173], v[172:173], v[122:123]
	v_pk_mul_f32 v[174:175], v[174:175], v[124:125]
	v_cvt_pk_bf16_f32 v228, v172, v173
	v_cvt_pk_bf16_f32 v229, v174, v175
	global_store_dwordx2 v[234:235], v[228:229], off
	s_waitcnt lgkmcnt(0)
	v_cndmask_b32_e64 v150, v70, v78, s[40:41]
	v_cndmask_b32_e64 v151, v71, v79, s[40:41]
	v_cndmask_b32_e64 v152, v72, v80, s[40:41]
	v_cndmask_b32_e64 v153, v73, v81, s[40:41]
	v_cndmask_b32_e64 v154, v70, v138, s[42:43]
	v_cndmask_b32_e64 v155, v71, v139, s[42:43]
	v_cndmask_b32_e64 v156, v72, v140, s[42:43]
	v_cndmask_b32_e64 v157, v73, v141, s[42:43]
	v_pk_fma_f32 v[122:123], v[70:71], v[198:199], v[220:221]
	v_pk_fma_f32 v[124:125], v[72:73], v[200:201], v[222:223]
	v_fmac_f32_dpp v122, v150, v190 row_ror:1 row_mask:0xf bank_mask:0xf
	v_fmac_f32_dpp v123, v151, v191 row_ror:1 row_mask:0xf bank_mask:0xf
	v_fmac_f32_dpp v124, v152, v192 row_ror:1 row_mask:0xf bank_mask:0xf
	v_fmac_f32_dpp v125, v153, v193 row_ror:1 row_mask:0xf bank_mask:0xf
	v_fmac_f32_dpp v122, v154, v212 row_ror:15 row_mask:0xf bank_mask:0xf
	v_fmac_f32_dpp v123, v155, v213 row_ror:15 row_mask:0xf bank_mask:0xf
	v_fmac_f32_dpp v124, v156, v214 row_ror:15 row_mask:0xf bank_mask:0xf
	v_fmac_f32_dpp v125, v157, v215 row_ror:15 row_mask:0xf bank_mask:0xf
	v_cndmask_b32_e64 v150, v66, v74, s[40:41]
	v_cndmask_b32_e64 v151, v67, v75, s[40:41]
	v_cndmask_b32_e64 v152, v68, v76, s[40:41]
	v_cndmask_b32_e64 v153, v69, v77, s[40:41]
	v_cndmask_b32_e64 v154, v66, v142, s[42:43]
	v_cndmask_b32_e64 v155, v67, v143, s[42:43]
	v_cndmask_b32_e64 v156, v68, v144, s[42:43]
	v_cndmask_b32_e64 v157, v69, v145, s[42:43]
	v_pk_fma_f32 v[158:159], v[66:67], v[208:209], v[224:225]
	v_pk_fma_f32 v[160:161], v[68:69], v[210:211], v[226:227]
	v_fmac_f32_dpp v158, v150, v194 row_ror:1 row_mask:0xf bank_mask:0xf
	v_fmac_f32_dpp v159, v151, v195 row_ror:1 row_mask:0xf bank_mask:0xf
	v_fmac_f32_dpp v160, v152, v196 row_ror:1 row_mask:0xf bank_mask:0xf
	v_fmac_f32_dpp v161, v153, v197 row_ror:1 row_mask:0xf bank_mask:0xf
	v_fmac_f32_dpp v158, v154, v216 row_ror:15 row_mask:0xf bank_mask:0xf
	v_fmac_f32_dpp v159, v155, v217 row_ror:15 row_mask:0xf bank_mask:0xf
	v_fmac_f32_dpp v160, v156, v218 row_ror:15 row_mask:0xf bank_mask:0xf
	v_fmac_f32_dpp v161, v157, v219 row_ror:15 row_mask:0xf bank_mask:0xf
	s_lshl_b32 s100, s30, 11
	s_add_i32 s100, s100, 0x800
	v_add_u32_e32 v231, s100, v189
	ds_read_b128 v[138:141], v231 offset:16
	ds_read_b128 v[142:145], v231 offset:528
	v_exp_f32_e32 v172, v122
	v_exp_f32_e32 v173, v123
	v_exp_f32_e32 v174, v124
	v_exp_f32_e32 v175, v125
	v_pk_add_f32 v[172:173], v[172:173], v[236:237] op_sel_hi:[1,0]
	v_pk_add_f32 v[174:175], v[174:175], v[236:237] op_sel_hi:[1,0]
	v_rcp_f32_e32 v172, v172
	v_rcp_f32_e32 v173, v173
	v_rcp_f32_e32 v174, v174
	v_rcp_f32_e32 v175, v175
	s_mov_b64 s[100:101], 0xf2000
	v_lshl_add_u64 v[234:235], v[232:233], 0, s[100:101]
	v_pk_mul_f32 v[122:123], v[122:123], v[158:159]
	v_pk_mul_f32 v[124:125], v[124:125], v[160:161]
	v_pk_mul_f32 v[172:173], v[172:173], v[122:123]
	v_pk_mul_f32 v[174:175], v[174:175], v[124:125]
	v_cvt_pk_bf16_f32 v228, v172, v173
	v_cvt_pk_bf16_f32 v229, v174, v175
	global_store_dwordx2 v[234:235], v[228:229], off
	s_waitcnt lgkmcnt(0)
	v_cndmask_b32_e64 v150, v62, v130, s[40:41]
	v_cndmask_b32_e64 v151, v63, v131, s[40:41]
	v_cndmask_b32_e64 v152, v64, v132, s[40:41]
	v_cndmask_b32_e64 v153, v65, v133, s[40:41]
	v_cndmask_b32_e64 v154, v62, v54, s[42:43]
	v_cndmask_b32_e64 v155, v63, v55, s[42:43]
	v_cndmask_b32_e64 v156, v64, v56, s[42:43]
	v_cndmask_b32_e64 v157, v65, v57, s[42:43]
	v_pk_fma_f32 v[122:123], v[62:63], v[118:119], v[102:103]
	v_pk_fma_f32 v[124:125], v[64:65], v[120:121], v[104:105]
	v_fmac_f32_dpp v122, v150, v126 row_ror:1 row_mask:0xf bank_mask:0xf
	v_fmac_f32_dpp v123, v151, v127 row_ror:1 row_mask:0xf bank_mask:0xf
	v_fmac_f32_dpp v124, v152, v128 row_ror:1 row_mask:0xf bank_mask:0xf
	v_fmac_f32_dpp v125, v153, v129 row_ror:1 row_mask:0xf bank_mask:0xf
	v_fmac_f32_dpp v122, v154, v110 row_ror:15 row_mask:0xf bank_mask:0xf
	v_fmac_f32_dpp v123, v155, v111 row_ror:15 row_mask:0xf bank_mask:0xf
	v_fmac_f32_dpp v124, v156, v112 row_ror:15 row_mask:0xf bank_mask:0xf
	v_fmac_f32_dpp v125, v157, v113 row_ror:15 row_mask:0xf bank_mask:0xf
	v_cndmask_b32_e64 v150, v58, v134, s[40:41]
	v_cndmask_b32_e64 v151, v59, v135, s[40:41]
	v_cndmask_b32_e64 v152, v60, v136, s[40:41]
	v_cndmask_b32_e64 v153, v61, v137, s[40:41]
	v_cndmask_b32_e64 v154, v58, v50, s[42:43]
	v_cndmask_b32_e64 v155, v59, v51, s[42:43]
	v_cndmask_b32_e64 v156, v60, v52, s[42:43]
	v_cndmask_b32_e64 v157, v61, v53, s[42:43]
	v_pk_fma_f32 v[158:159], v[58:59], v[114:115], v[98:99]
	v_pk_fma_f32 v[160:161], v[60:61], v[116:117], v[100:101]
	v_fmac_f32_dpp v158, v150, v146 row_ror:1 row_mask:0xf bank_mask:0xf
	v_fmac_f32_dpp v159, v151, v147 row_ror:1 row_mask:0xf bank_mask:0xf
	v_fmac_f32_dpp v160, v152, v148 row_ror:1 row_mask:0xf bank_mask:0xf
	v_fmac_f32_dpp v161, v153, v149 row_ror:1 row_mask:0xf bank_mask:0xf
	v_fmac_f32_dpp v158, v154, v106 row_ror:15 row_mask:0xf bank_mask:0xf
	v_fmac_f32_dpp v159, v155, v107 row_ror:15 row_mask:0xf bank_mask:0xf
	v_fmac_f32_dpp v160, v156, v108 row_ror:15 row_mask:0xf bank_mask:0xf
	v_fmac_f32_dpp v161, v157, v109 row_ror:15 row_mask:0xf bank_mask:0xf
	s_lshl_b32 s100, s30, 11
	s_add_i32 s100, s100, 0xc00
	v_add_u32_e32 v231, s100, v189
	ds_read_b128 v[130:133], v231 offset:16
	ds_read_b128 v[134:137], v231 offset:528
	v_exp_f32_e32 v172, v122
	v_exp_f32_e32 v173, v123
	v_exp_f32_e32 v174, v124
	v_exp_f32_e32 v175, v125
	v_pk_add_f32 v[172:173], v[172:173], v[236:237] op_sel_hi:[1,0]
	v_pk_add_f32 v[174:175], v[174:175], v[236:237] op_sel_hi:[1,0]
	v_rcp_f32_e32 v172, v172
	v_rcp_f32_e32 v173, v173
	v_rcp_f32_e32 v174, v174
	v_rcp_f32_e32 v175, v175
	v_mov_b64_e32 v[234:235], v[232:233]
	v_pk_mul_f32 v[122:123], v[122:123], v[158:159]
	v_pk_mul_f32 v[124:125], v[124:125], v[160:161]
	v_pk_mul_f32 v[172:173], v[172:173], v[122:123]
	v_pk_mul_f32 v[174:175], v[174:175], v[124:125]
	v_cvt_pk_bf16_f32 v228, v172, v173
	v_cvt_pk_bf16_f32 v229, v174, v175
	global_store_dwordx2 v[234:235], v[228:229], off offset:8
	v_cndmask_b32_e64 v150, v54, v62, s[40:41]
	v_cndmask_b32_e64 v151, v55, v63, s[40:41]
	v_cndmask_b32_e64 v152, v56, v64, s[40:41]
	v_cndmask_b32_e64 v153, v57, v65, s[40:41]
	v_cndmask_b32_e64 v154, v54, v46, s[42:43]
	v_cndmask_b32_e64 v155, v55, v47, s[42:43]
	v_cndmask_b32_e64 v156, v56, v48, s[42:43]
	v_cndmask_b32_e64 v157, v57, v49, s[42:43]
	v_pk_fma_f32 v[122:123], v[54:55], v[118:119], v[102:103]
	v_pk_fma_f32 v[124:125], v[56:57], v[120:121], v[104:105]
	v_fmac_f32_dpp v122, v150, v126 row_ror:1 row_mask:0xf bank_mask:0xf
	v_fmac_f32_dpp v123, v151, v127 row_ror:1 row_mask:0xf bank_mask:0xf
	v_fmac_f32_dpp v124, v152, v128 row_ror:1 row_mask:0xf bank_mask:0xf
	v_fmac_f32_dpp v125, v153, v129 row_ror:1 row_mask:0xf bank_mask:0xf
	v_fmac_f32_dpp v122, v154, v110 row_ror:15 row_mask:0xf bank_mask:0xf
	v_fmac_f32_dpp v123, v155, v111 row_ror:15 row_mask:0xf bank_mask:0xf
	v_fmac_f32_dpp v124, v156, v112 row_ror:15 row_mask:0xf bank_mask:0xf
	v_fmac_f32_dpp v125, v157, v113 row_ror:15 row_mask:0xf bank_mask:0xf
	v_cndmask_b32_e64 v150, v50, v58, s[40:41]
	v_cndmask_b32_e64 v151, v51, v59, s[40:41]
	v_cndmask_b32_e64 v152, v52, v60, s[40:41]
	v_cndmask_b32_e64 v153, v53, v61, s[40:41]
	v_cndmask_b32_e64 v154, v50, v42, s[42:43]
	v_cndmask_b32_e64 v155, v51, v43, s[42:43]
	v_cndmask_b32_e64 v156, v52, v44, s[42:43]
	v_cndmask_b32_e64 v157, v53, v45, s[42:43]
	v_pk_fma_f32 v[158:159], v[50:51], v[114:115], v[98:99]
	v_pk_fma_f32 v[160:161], v[52:53], v[116:117], v[100:101]
	v_fmac_f32_dpp v158, v150, v146 row_ror:1 row_mask:0xf bank_mask:0xf
	v_fmac_f32_dpp v159, v151, v147 row_ror:1 row_mask:0xf bank_mask:0xf
	v_fmac_f32_dpp v160, v152, v148 row_ror:1 row_mask:0xf bank_mask:0xf
	v_fmac_f32_dpp v161, v153, v149 row_ror:1 row_mask:0xf bank_mask:0xf
	v_fmac_f32_dpp v158, v154, v106 row_ror:15 row_mask:0xf bank_mask:0xf
	v_fmac_f32_dpp v159, v155, v107 row_ror:15 row_mask:0xf bank_mask:0xf
	v_fmac_f32_dpp v160, v156, v108 row_ror:15 row_mask:0xf bank_mask:0xf
	v_fmac_f32_dpp v161, v157, v109 row_ror:15 row_mask:0xf bank_mask:0xf
	v_exp_f32_e32 v172, v122
	v_exp_f32_e32 v173, v123
	v_exp_f32_e32 v174, v124
	v_exp_f32_e32 v175, v125
	v_pk_add_f32 v[172:173], v[172:173], v[236:237] op_sel_hi:[1,0]
	v_pk_add_f32 v[174:175], v[174:175], v[236:237] op_sel_hi:[1,0]
	v_rcp_f32_e32 v172, v172
	v_rcp_f32_e32 v173, v173
	v_rcp_f32_e32 v174, v174
	v_rcp_f32_e32 v175, v175
	s_mov_b64 s[100:101], 0x16000
	v_lshl_add_u64 v[234:235], v[232:233], 0, s[100:101]
	v_pk_mul_f32 v[122:123], v[122:123], v[158:159]
	v_pk_mul_f32 v[124:125], v[124:125], v[160:161]
	v_pk_mul_f32 v[172:173], v[172:173], v[122:123]
	v_pk_mul_f32 v[174:175], v[174:175], v[124:125]
	v_cvt_pk_bf16_f32 v228, v172, v173
	v_cvt_pk_bf16_f32 v229, v174, v175
	global_store_dwordx2 v[234:235], v[228:229], off offset:8
	v_cndmask_b32_e64 v150, v46, v54, s[40:41]
	v_cndmask_b32_e64 v151, v47, v55, s[40:41]
	v_cndmask_b32_e64 v152, v48, v56, s[40:41]
	v_cndmask_b32_e64 v153, v49, v57, s[40:41]
	v_cndmask_b32_e64 v154, v46, v38, s[42:43]
	v_cndmask_b32_e64 v155, v47, v39, s[42:43]
	v_cndmask_b32_e64 v156, v48, v40, s[42:43]
	v_cndmask_b32_e64 v157, v49, v41, s[42:43]
	v_pk_fma_f32 v[122:123], v[46:47], v[118:119], v[102:103]
	v_pk_fma_f32 v[124:125], v[48:49], v[120:121], v[104:105]
	v_fmac_f32_dpp v122, v150, v126 row_ror:1 row_mask:0xf bank_mask:0xf
	v_fmac_f32_dpp v123, v151, v127 row_ror:1 row_mask:0xf bank_mask:0xf
	v_fmac_f32_dpp v124, v152, v128 row_ror:1 row_mask:0xf bank_mask:0xf
	v_fmac_f32_dpp v125, v153, v129 row_ror:1 row_mask:0xf bank_mask:0xf
	v_fmac_f32_dpp v122, v154, v110 row_ror:15 row_mask:0xf bank_mask:0xf
	v_fmac_f32_dpp v123, v155, v111 row_ror:15 row_mask:0xf bank_mask:0xf
	v_fmac_f32_dpp v124, v156, v112 row_ror:15 row_mask:0xf bank_mask:0xf
	v_fmac_f32_dpp v125, v157, v113 row_ror:15 row_mask:0xf bank_mask:0xf
	v_cndmask_b32_e64 v150, v42, v50, s[40:41]
	v_cndmask_b32_e64 v151, v43, v51, s[40:41]
	v_cndmask_b32_e64 v152, v44, v52, s[40:41]
	v_cndmask_b32_e64 v153, v45, v53, s[40:41]
	v_cndmask_b32_e64 v154, v42, v34, s[42:43]
	v_cndmask_b32_e64 v155, v43, v35, s[42:43]
	v_cndmask_b32_e64 v156, v44, v36, s[42:43]
	v_cndmask_b32_e64 v157, v45, v37, s[42:43]
	v_pk_fma_f32 v[158:159], v[42:43], v[114:115], v[98:99]
	v_pk_fma_f32 v[160:161], v[44:45], v[116:117], v[100:101]
	v_fmac_f32_dpp v158, v150, v146 row_ror:1 row_mask:0xf bank_mask:0xf
	v_fmac_f32_dpp v159, v151, v147 row_ror:1 row_mask:0xf bank_mask:0xf
	v_fmac_f32_dpp v160, v152, v148 row_ror:1 row_mask:0xf bank_mask:0xf
	v_fmac_f32_dpp v161, v153, v149 row_ror:1 row_mask:0xf bank_mask:0xf
	v_fmac_f32_dpp v158, v154, v106 row_ror:15 row_mask:0xf bank_mask:0xf
	v_fmac_f32_dpp v159, v155, v107 row_ror:15 row_mask:0xf bank_mask:0xf
	v_fmac_f32_dpp v160, v156, v108 row_ror:15 row_mask:0xf bank_mask:0xf
	v_fmac_f32_dpp v161, v157, v109 row_ror:15 row_mask:0xf bank_mask:0xf
	v_exp_f32_e32 v172, v122
	v_exp_f32_e32 v173, v123
	v_exp_f32_e32 v174, v124
	v_exp_f32_e32 v175, v125
	v_pk_add_f32 v[172:173], v[172:173], v[236:237] op_sel_hi:[1,0]
	v_pk_add_f32 v[174:175], v[174:175], v[236:237] op_sel_hi:[1,0]
	v_rcp_f32_e32 v172, v172
	v_rcp_f32_e32 v173, v173
	v_rcp_f32_e32 v174, v174
	v_rcp_f32_e32 v175, v175
	s_mov_b64 s[100:101], 0x2c000
	v_lshl_add_u64 v[234:235], v[232:233], 0, s[100:101]
	v_pk_mul_f32 v[122:123], v[122:123], v[158:159]
	v_pk_mul_f32 v[124:125], v[124:125], v[160:161]
	v_pk_mul_f32 v[172:173], v[172:173], v[122:123]
	v_pk_mul_f32 v[174:175], v[174:175], v[124:125]
	v_cvt_pk_bf16_f32 v228, v172, v173
	v_cvt_pk_bf16_f32 v229, v174, v175
	global_store_dwordx2 v[234:235], v[228:229], off offset:8
	s_waitcnt lgkmcnt(0)
	v_cndmask_b32_e64 v150, v38, v46, s[40:41]
	v_cndmask_b32_e64 v151, v39, v47, s[40:41]
	v_cndmask_b32_e64 v152, v40, v48, s[40:41]
	v_cndmask_b32_e64 v153, v41, v49, s[40:41]
	v_cndmask_b32_e64 v154, v38, v138, s[42:43]
	v_cndmask_b32_e64 v155, v39, v139, s[42:43]
	v_cndmask_b32_e64 v156, v40, v140, s[42:43]
	v_cndmask_b32_e64 v157, v41, v141, s[42:43]
	v_pk_fma_f32 v[122:123], v[38:39], v[118:119], v[102:103]
	v_pk_fma_f32 v[124:125], v[40:41], v[120:121], v[104:105]
	v_fmac_f32_dpp v122, v150, v126 row_ror:1 row_mask:0xf bank_mask:0xf
	v_fmac_f32_dpp v123, v151, v127 row_ror:1 row_mask:0xf bank_mask:0xf
	v_fmac_f32_dpp v124, v152, v128 row_ror:1 row_mask:0xf bank_mask:0xf
	v_fmac_f32_dpp v125, v153, v129 row_ror:1 row_mask:0xf bank_mask:0xf
	v_fmac_f32_dpp v122, v154, v110 row_ror:15 row_mask:0xf bank_mask:0xf
	v_fmac_f32_dpp v123, v155, v111 row_ror:15 row_mask:0xf bank_mask:0xf
	v_fmac_f32_dpp v124, v156, v112 row_ror:15 row_mask:0xf bank_mask:0xf
	v_fmac_f32_dpp v125, v157, v113 row_ror:15 row_mask:0xf bank_mask:0xf
	v_cndmask_b32_e64 v150, v34, v42, s[40:41]
	v_cndmask_b32_e64 v151, v35, v43, s[40:41]
	v_cndmask_b32_e64 v152, v36, v44, s[40:41]
	v_cndmask_b32_e64 v153, v37, v45, s[40:41]
	v_cndmask_b32_e64 v154, v34, v142, s[42:43]
	v_cndmask_b32_e64 v155, v35, v143, s[42:43]
	v_cndmask_b32_e64 v156, v36, v144, s[42:43]
	v_cndmask_b32_e64 v157, v37, v145, s[42:43]
	v_pk_fma_f32 v[158:159], v[34:35], v[114:115], v[98:99]
	v_pk_fma_f32 v[160:161], v[36:37], v[116:117], v[100:101]
	v_fmac_f32_dpp v158, v150, v146 row_ror:1 row_mask:0xf bank_mask:0xf
	v_fmac_f32_dpp v159, v151, v147 row_ror:1 row_mask:0xf bank_mask:0xf
	v_fmac_f32_dpp v160, v152, v148 row_ror:1 row_mask:0xf bank_mask:0xf
	v_fmac_f32_dpp v161, v153, v149 row_ror:1 row_mask:0xf bank_mask:0xf
	v_fmac_f32_dpp v158, v154, v106 row_ror:15 row_mask:0xf bank_mask:0xf
	v_fmac_f32_dpp v159, v155, v107 row_ror:15 row_mask:0xf bank_mask:0xf
	v_fmac_f32_dpp v160, v156, v108 row_ror:15 row_mask:0xf bank_mask:0xf
	v_fmac_f32_dpp v161, v157, v109 row_ror:15 row_mask:0xf bank_mask:0xf
	s_cmp_eq_u32 s30, 1
	s_cbranch_scc1 .Lffn1c_7
	s_lshl_b32 s100, s30, 11
	s_add_i32 s100, s100, 0x1800
	v_add_u32_e32 v231, s100, v189
	ds_read_b128 v[138:141], v231 offset:16
	ds_read_b128 v[142:145], v231 offset:528
	s_branch .Lffn1c_8

.Lffn1c_8:
	v_exp_f32_e32 v172, v122
	v_exp_f32_e32 v173, v123
	v_exp_f32_e32 v174, v124
	v_exp_f32_e32 v175, v125
	v_pk_add_f32 v[172:173], v[172:173], v[236:237] op_sel_hi:[1,0]
	v_pk_add_f32 v[174:175], v[174:175], v[236:237] op_sel_hi:[1,0]
	v_rcp_f32_e32 v172, v172
	v_rcp_f32_e32 v173, v173
	v_rcp_f32_e32 v174, v174
	v_rcp_f32_e32 v175, v175
	s_mov_b64 s[100:101], 0x42000
	v_lshl_add_u64 v[234:235], v[232:233], 0, s[100:101]
	v_pk_mul_f32 v[122:123], v[122:123], v[158:159]
	v_pk_mul_f32 v[124:125], v[124:125], v[160:161]
	v_pk_mul_f32 v[172:173], v[172:173], v[122:123]
	v_pk_mul_f32 v[174:175], v[174:175], v[124:125]
	v_cvt_pk_bf16_f32 v228, v172, v173
	v_cvt_pk_bf16_f32 v229, v174, v175
	global_store_dwordx2 v[234:235], v[228:229], off offset:8
	s_waitcnt lgkmcnt(0)
	v_cndmask_b32_e64 v150, v30, v130, s[40:41]
	v_cndmask_b32_e64 v151, v31, v131, s[40:41]
	v_cndmask_b32_e64 v152, v32, v132, s[40:41]
	v_cndmask_b32_e64 v153, v33, v133, s[40:41]
	v_cndmask_b32_e64 v154, v30, v22, s[42:43]
	v_cndmask_b32_e64 v155, v31, v23, s[42:43]
	v_cndmask_b32_e64 v156, v32, v24, s[42:43]
	v_cndmask_b32_e64 v157, v33, v25, s[42:43]
	v_pk_fma_f32 v[122:123], v[30:31], v[118:119], v[102:103]
	v_pk_fma_f32 v[124:125], v[32:33], v[120:121], v[104:105]
	v_fmac_f32_dpp v122, v150, v126 row_ror:1 row_mask:0xf bank_mask:0xf
	v_fmac_f32_dpp v123, v151, v127 row_ror:1 row_mask:0xf bank_mask:0xf
	v_fmac_f32_dpp v124, v152, v128 row_ror:1 row_mask:0xf bank_mask:0xf
	v_fmac_f32_dpp v125, v153, v129 row_ror:1 row_mask:0xf bank_mask:0xf
	v_fmac_f32_dpp v122, v154, v110 row_ror:15 row_mask:0xf bank_mask:0xf
	v_fmac_f32_dpp v123, v155, v111 row_ror:15 row_mask:0xf bank_mask:0xf
	v_fmac_f32_dpp v124, v156, v112 row_ror:15 row_mask:0xf bank_mask:0xf
	v_fmac_f32_dpp v125, v157, v113 row_ror:15 row_mask:0xf bank_mask:0xf
	v_cndmask_b32_e64 v150, v26, v134, s[40:41]
	v_cndmask_b32_e64 v151, v27, v135, s[40:41]
	v_cndmask_b32_e64 v152, v28, v136, s[40:41]
	v_cndmask_b32_e64 v153, v29, v137, s[40:41]
	v_cndmask_b32_e64 v154, v26, v18, s[42:43]
	v_cndmask_b32_e64 v155, v27, v19, s[42:43]
	v_cndmask_b32_e64 v156, v28, v20, s[42:43]
	v_cndmask_b32_e64 v157, v29, v21, s[42:43]
	v_pk_fma_f32 v[158:159], v[26:27], v[114:115], v[98:99]
	v_pk_fma_f32 v[160:161], v[28:29], v[116:117], v[100:101]
	v_fmac_f32_dpp v158, v150, v146 row_ror:1 row_mask:0xf bank_mask:0xf
	v_fmac_f32_dpp v159, v151, v147 row_ror:1 row_mask:0xf bank_mask:0xf
	v_fmac_f32_dpp v160, v152, v148 row_ror:1 row_mask:0xf bank_mask:0xf
	v_fmac_f32_dpp v161, v153, v149 row_ror:1 row_mask:0xf bank_mask:0xf
	v_fmac_f32_dpp v158, v154, v106 row_ror:15 row_mask:0xf bank_mask:0xf
	v_fmac_f32_dpp v159, v155, v107 row_ror:15 row_mask:0xf bank_mask:0xf
	v_fmac_f32_dpp v160, v156, v108 row_ror:15 row_mask:0xf bank_mask:0xf
	v_fmac_f32_dpp v161, v157, v109 row_ror:15 row_mask:0xf bank_mask:0xf
	v_exp_f32_e32 v172, v122
	v_exp_f32_e32 v173, v123
	v_exp_f32_e32 v174, v124
	v_exp_f32_e32 v175, v125
	v_pk_add_f32 v[172:173], v[172:173], v[236:237] op_sel_hi:[1,0]
	v_pk_add_f32 v[174:175], v[174:175], v[236:237] op_sel_hi:[1,0]
	v_rcp_f32_e32 v172, v172
	v_rcp_f32_e32 v173, v173
	v_rcp_f32_e32 v174, v174
	v_rcp_f32_e32 v175, v175
	s_mov_b64 s[100:101], 0xb0000
	v_lshl_add_u64 v[234:235], v[232:233], 0, s[100:101]
	v_pk_mul_f32 v[122:123], v[122:123], v[158:159]
	v_pk_mul_f32 v[124:125], v[124:125], v[160:161]
	v_pk_mul_f32 v[172:173], v[172:173], v[122:123]
	v_pk_mul_f32 v[174:175], v[174:175], v[124:125]
	v_cvt_pk_bf16_f32 v228, v172, v173
	v_cvt_pk_bf16_f32 v229, v174, v175
	global_store_dwordx2 v[234:235], v[228:229], off offset:8
	v_cndmask_b32_e64 v150, v22, v30, s[40:41]
	v_cndmask_b32_e64 v151, v23, v31, s[40:41]
	v_cndmask_b32_e64 v152, v24, v32, s[40:41]
	v_cndmask_b32_e64 v153, v25, v33, s[40:41]
	v_cndmask_b32_e64 v154, v22, v14, s[42:43]
	v_cndmask_b32_e64 v155, v23, v15, s[42:43]
	v_cndmask_b32_e64 v156, v24, v16, s[42:43]
	v_cndmask_b32_e64 v157, v25, v17, s[42:43]
	v_pk_fma_f32 v[122:123], v[22:23], v[118:119], v[102:103]
	v_pk_fma_f32 v[124:125], v[24:25], v[120:121], v[104:105]
	v_fmac_f32_dpp v122, v150, v126 row_ror:1 row_mask:0xf bank_mask:0xf
	v_fmac_f32_dpp v123, v151, v127 row_ror:1 row_mask:0xf bank_mask:0xf
	v_fmac_f32_dpp v124, v152, v128 row_ror:1 row_mask:0xf bank_mask:0xf
	v_fmac_f32_dpp v125, v153, v129 row_ror:1 row_mask:0xf bank_mask:0xf
	v_fmac_f32_dpp v122, v154, v110 row_ror:15 row_mask:0xf bank_mask:0xf
	v_fmac_f32_dpp v123, v155, v111 row_ror:15 row_mask:0xf bank_mask:0xf
	v_fmac_f32_dpp v124, v156, v112 row_ror:15 row_mask:0xf bank_mask:0xf
	v_fmac_f32_dpp v125, v157, v113 row_ror:15 row_mask:0xf bank_mask:0xf
	v_cndmask_b32_e64 v150, v18, v26, s[40:41]
	v_cndmask_b32_e64 v151, v19, v27, s[40:41]
	v_cndmask_b32_e64 v152, v20, v28, s[40:41]
	v_cndmask_b32_e64 v153, v21, v29, s[40:41]
	v_cndmask_b32_e64 v154, v18, v10, s[42:43]
	v_cndmask_b32_e64 v155, v19, v11, s[42:43]
	v_cndmask_b32_e64 v156, v20, v12, s[42:43]
	v_cndmask_b32_e64 v157, v21, v13, s[42:43]
	v_pk_fma_f32 v[158:159], v[18:19], v[114:115], v[98:99]
	v_pk_fma_f32 v[160:161], v[20:21], v[116:117], v[100:101]
	v_fmac_f32_dpp v158, v150, v146 row_ror:1 row_mask:0xf bank_mask:0xf
	v_fmac_f32_dpp v159, v151, v147 row_ror:1 row_mask:0xf bank_mask:0xf
	v_fmac_f32_dpp v160, v152, v148 row_ror:1 row_mask:0xf bank_mask:0xf
	v_fmac_f32_dpp v161, v153, v149 row_ror:1 row_mask:0xf bank_mask:0xf
	v_fmac_f32_dpp v158, v154, v106 row_ror:15 row_mask:0xf bank_mask:0xf
	v_fmac_f32_dpp v159, v155, v107 row_ror:15 row_mask:0xf bank_mask:0xf
	v_fmac_f32_dpp v160, v156, v108 row_ror:15 row_mask:0xf bank_mask:0xf
	v_fmac_f32_dpp v161, v157, v109 row_ror:15 row_mask:0xf bank_mask:0xf
	v_exp_f32_e32 v172, v122
	v_exp_f32_e32 v173, v123
	v_exp_f32_e32 v174, v124
	v_exp_f32_e32 v175, v125
	v_pk_add_f32 v[172:173], v[172:173], v[236:237] op_sel_hi:[1,0]
	v_pk_add_f32 v[174:175], v[174:175], v[236:237] op_sel_hi:[1,0]
	v_rcp_f32_e32 v172, v172
	v_rcp_f32_e32 v173, v173
	v_rcp_f32_e32 v174, v174
	v_rcp_f32_e32 v175, v175
	s_mov_b64 s[100:101], 0xc6000
	v_lshl_add_u64 v[234:235], v[232:233], 0, s[100:101]
	v_pk_mul_f32 v[122:123], v[122:123], v[158:159]
	v_pk_mul_f32 v[124:125], v[124:125], v[160:161]
	v_pk_mul_f32 v[172:173], v[172:173], v[122:123]
	v_pk_mul_f32 v[174:175], v[174:175], v[124:125]
	v_cvt_pk_bf16_f32 v228, v172, v173
	v_cvt_pk_bf16_f32 v229, v174, v175
	global_store_dwordx2 v[234:235], v[228:229], off offset:8
	v_cndmask_b32_e64 v150, v14, v22, s[40:41]
	v_cndmask_b32_e64 v151, v15, v23, s[40:41]
	v_cndmask_b32_e64 v152, v16, v24, s[40:41]
	v_cndmask_b32_e64 v153, v17, v25, s[40:41]
	v_cndmask_b32_e64 v154, v14, v6, s[42:43]
	v_cndmask_b32_e64 v155, v15, v7, s[42:43]
	v_cndmask_b32_e64 v156, v16, v8, s[42:43]
	v_cndmask_b32_e64 v157, v17, v9, s[42:43]
	v_pk_fma_f32 v[122:123], v[14:15], v[118:119], v[102:103]
	v_pk_fma_f32 v[124:125], v[16:17], v[120:121], v[104:105]
	v_fmac_f32_dpp v122, v150, v126 row_ror:1 row_mask:0xf bank_mask:0xf
	v_fmac_f32_dpp v123, v151, v127 row_ror:1 row_mask:0xf bank_mask:0xf
	v_fmac_f32_dpp v124, v152, v128 row_ror:1 row_mask:0xf bank_mask:0xf
	v_fmac_f32_dpp v125, v153, v129 row_ror:1 row_mask:0xf bank_mask:0xf
	v_fmac_f32_dpp v122, v154, v110 row_ror:15 row_mask:0xf bank_mask:0xf
	v_fmac_f32_dpp v123, v155, v111 row_ror:15 row_mask:0xf bank_mask:0xf
	v_fmac_f32_dpp v124, v156, v112 row_ror:15 row_mask:0xf bank_mask:0xf
	v_fmac_f32_dpp v125, v157, v113 row_ror:15 row_mask:0xf bank_mask:0xf
	v_cndmask_b32_e64 v150, v10, v18, s[40:41]
	v_cndmask_b32_e64 v151, v11, v19, s[40:41]
	v_cndmask_b32_e64 v152, v12, v20, s[40:41]
	v_cndmask_b32_e64 v153, v13, v21, s[40:41]
	v_cndmask_b32_e64 v154, v10, v2, s[42:43]
	v_cndmask_b32_e64 v155, v11, v3, s[42:43]
	v_cndmask_b32_e64 v156, v12, v4, s[42:43]
	v_cndmask_b32_e64 v157, v13, v5, s[42:43]
	v_pk_fma_f32 v[158:159], v[10:11], v[114:115], v[98:99]
	v_pk_fma_f32 v[160:161], v[12:13], v[116:117], v[100:101]
	v_fmac_f32_dpp v158, v150, v146 row_ror:1 row_mask:0xf bank_mask:0xf
	v_fmac_f32_dpp v159, v151, v147 row_ror:1 row_mask:0xf bank_mask:0xf
	v_fmac_f32_dpp v160, v152, v148 row_ror:1 row_mask:0xf bank_mask:0xf
	v_fmac_f32_dpp v161, v153, v149 row_ror:1 row_mask:0xf bank_mask:0xf
	v_fmac_f32_dpp v158, v154, v106 row_ror:15 row_mask:0xf bank_mask:0xf
	v_fmac_f32_dpp v159, v155, v107 row_ror:15 row_mask:0xf bank_mask:0xf
	v_fmac_f32_dpp v160, v156, v108 row_ror:15 row_mask:0xf bank_mask:0xf
	v_fmac_f32_dpp v161, v157, v109 row_ror:15 row_mask:0xf bank_mask:0xf
	v_exp_f32_e32 v172, v122
	v_exp_f32_e32 v173, v123
	v_exp_f32_e32 v174, v124
	v_exp_f32_e32 v175, v125
	v_pk_add_f32 v[172:173], v[172:173], v[236:237] op_sel_hi:[1,0]
	v_pk_add_f32 v[174:175], v[174:175], v[236:237] op_sel_hi:[1,0]
	v_rcp_f32_e32 v172, v172
	v_rcp_f32_e32 v173, v173
	v_rcp_f32_e32 v174, v174
	v_rcp_f32_e32 v175, v175
	s_mov_b64 s[100:101], 0xdc000
	v_lshl_add_u64 v[234:235], v[232:233], 0, s[100:101]
	v_pk_mul_f32 v[122:123], v[122:123], v[158:159]
	v_pk_mul_f32 v[124:125], v[124:125], v[160:161]
	v_pk_mul_f32 v[172:173], v[172:173], v[122:123]
	v_pk_mul_f32 v[174:175], v[174:175], v[124:125]
	v_cvt_pk_bf16_f32 v228, v172, v173
	v_cvt_pk_bf16_f32 v229, v174, v175
	global_store_dwordx2 v[234:235], v[228:229], off offset:8
	s_waitcnt lgkmcnt(0)
	v_cndmask_b32_e64 v150, v6, v14, s[40:41]
	v_cndmask_b32_e64 v151, v7, v15, s[40:41]
	v_cndmask_b32_e64 v152, v8, v16, s[40:41]
	v_cndmask_b32_e64 v153, v9, v17, s[40:41]
	v_cndmask_b32_e64 v154, v6, v138, s[42:43]
	v_cndmask_b32_e64 v155, v7, v139, s[42:43]
	v_cndmask_b32_e64 v156, v8, v140, s[42:43]
	v_cndmask_b32_e64 v157, v9, v141, s[42:43]
	v_pk_fma_f32 v[122:123], v[6:7], v[118:119], v[102:103]
	v_pk_fma_f32 v[124:125], v[8:9], v[120:121], v[104:105]
	v_fmac_f32_dpp v122, v150, v126 row_ror:1 row_mask:0xf bank_mask:0xf
	v_fmac_f32_dpp v123, v151, v127 row_ror:1 row_mask:0xf bank_mask:0xf
	v_fmac_f32_dpp v124, v152, v128 row_ror:1 row_mask:0xf bank_mask:0xf
	v_fmac_f32_dpp v125, v153, v129 row_ror:1 row_mask:0xf bank_mask:0xf
	v_fmac_f32_dpp v122, v154, v110 row_ror:15 row_mask:0xf bank_mask:0xf
	v_fmac_f32_dpp v123, v155, v111 row_ror:15 row_mask:0xf bank_mask:0xf
	v_fmac_f32_dpp v124, v156, v112 row_ror:15 row_mask:0xf bank_mask:0xf
	v_fmac_f32_dpp v125, v157, v113 row_ror:15 row_mask:0xf bank_mask:0xf
	v_cndmask_b32_e64 v150, v2, v10, s[40:41]
	v_cndmask_b32_e64 v151, v3, v11, s[40:41]
	v_cndmask_b32_e64 v152, v4, v12, s[40:41]
	v_cndmask_b32_e64 v153, v5, v13, s[40:41]
	v_cndmask_b32_e64 v154, v2, v142, s[42:43]
	v_cndmask_b32_e64 v155, v3, v143, s[42:43]
	v_cndmask_b32_e64 v156, v4, v144, s[42:43]
	v_cndmask_b32_e64 v157, v5, v145, s[42:43]
	v_pk_fma_f32 v[158:159], v[2:3], v[114:115], v[98:99]
	v_pk_fma_f32 v[160:161], v[4:5], v[116:117], v[100:101]
	v_fmac_f32_dpp v158, v150, v146 row_ror:1 row_mask:0xf bank_mask:0xf
	v_fmac_f32_dpp v159, v151, v147 row_ror:1 row_mask:0xf bank_mask:0xf
	v_fmac_f32_dpp v160, v152, v148 row_ror:1 row_mask:0xf bank_mask:0xf
	v_fmac_f32_dpp v161, v153, v149 row_ror:1 row_mask:0xf bank_mask:0xf
	v_fmac_f32_dpp v158, v154, v106 row_ror:15 row_mask:0xf bank_mask:0xf
	v_fmac_f32_dpp v159, v155, v107 row_ror:15 row_mask:0xf bank_mask:0xf
	v_fmac_f32_dpp v160, v156, v108 row_ror:15 row_mask:0xf bank_mask:0xf
	v_fmac_f32_dpp v161, v157, v109 row_ror:15 row_mask:0xf bank_mask:0xf
	v_exp_f32_e32 v172, v122
	v_exp_f32_e32 v173, v123
	v_exp_f32_e32 v174, v124
	v_exp_f32_e32 v175, v125
	v_pk_add_f32 v[172:173], v[172:173], v[236:237] op_sel_hi:[1,0]
	v_pk_add_f32 v[174:175], v[174:175], v[236:237] op_sel_hi:[1,0]
	v_rcp_f32_e32 v172, v172
	v_rcp_f32_e32 v173, v173
	v_rcp_f32_e32 v174, v174
	v_rcp_f32_e32 v175, v175
	s_mov_b64 s[100:101], 0xf2000
	v_lshl_add_u64 v[234:235], v[232:233], 0, s[100:101]
	v_pk_mul_f32 v[122:123], v[122:123], v[158:159]
	v_pk_mul_f32 v[124:125], v[124:125], v[160:161]
	v_pk_mul_f32 v[172:173], v[172:173], v[122:123]
	v_pk_mul_f32 v[174:175], v[174:175], v[124:125]
	v_cvt_pk_bf16_f32 v228, v172, v173
	v_cvt_pk_bf16_f32 v229, v174, v175
	global_store_dwordx2 v[234:235], v[228:229], off offset:8
	s_and_b64 vcc, exec, s[38:39]
	s_mov_b64 s[0:1], -1
	s_cbranch_vccnz .LBB0_64
	s_andn2_b64 vcc, exec, s[6:7]
	s_cbranch_vccnz .LBB0_63
	s_barrier
	s_branch .LBB0_63
